# flash prologue de-serialisation: dead rpb table load loop skipped, Q-load drain merged with first K/V tile wait (both flash units), peeled first MLA chunk no longer drains vmcnt(0)
# baseline (speedup 1.0000x reference)
.LBB0_223:
	s_cmp_lt_i32 s25, 1
	v_mov_b32_e32 v2, v196
	s_cselect_b64 s[6:7], -1, 0
	s_cmp_gt_i32 s25, 0
	s_movk_i32 s2, 0x1d1
	s_cselect_b64 s[8:9], -1, 0
	v_cmp_gt_i32_e32 vcc, s2, v2
	s_and_b64 s[10:11], s[8:9], vcc
	s_and_saveexec_b64 s[8:9], s[10:11]
	s_branch .LBB0_231
	v_max_i32_e32 v0, 0xd1, v2
	v_sub_u32_e32 v0, v0, v2
	v_add_u32_e32 v0, 0xff, v0
	s_movk_i32 s2, 0xff
	v_cmp_lt_u32_e32 vcc, s2, v0
	s_mov_b64 s[12:13], -1
	v_mov_b32_e32 v4, v2
	s_and_saveexec_b64 s[10:11], vcc
	s_cbranch_execz .LBB0_228
	v_lshrrev_b32_e32 v0, 8, v0
	v_add_u32_e32 v0, 1, v0
	v_and_b32_e32 v6, 0x1fffffe, v0
	v_add_u32_e32 v3, 0x100, v2
	s_add_i32 s2, 0, 0xc000
	v_lshl_add_u32 v7, v2, 2, s2
	s_mov_b64 s[12:13], 0
	v_mov_b32_e32 v8, v6
	v_mov_b64_e32 v[4:5], v[2:3]

.LBB0_231:
	s_or_b64 exec, exec, s[8:9]
	v_and_b32_e32 v3, 15, v2
	v_ashrrev_i32_e32 v20, 1, v2
	s_movk_i32 s0, 0xffe0
	v_and_or_b32 v148, v20, s0, v3
	v_bfe_u32 v21, v2, 4, 2
	v_readlane_b32 s0, v224, 22
	v_or_b32_e32 v150, 16, v148
	v_lshlrev_b32_e32 v0, 4, v21
	v_readlane_b32 s1, v224, 23
	v_ashrrev_i32_e32 v149, 31, v148
	v_ashrrev_i32_e32 v151, 31, v150
	v_lshl_add_u64 v[12:13], s[0:1], 0, v[0:1]
	v_lshlrev_b64 v[4:5], 10, v[148:149]
	v_lshlrev_b64 v[14:15], 10, v[150:151]
	v_lshl_add_u64 v[8:9], v[12:13], 0, v[4:5]
	v_lshl_add_u64 v[16:17], v[12:13], 0, v[14:15]
	global_load_dwordx4 v[4:7], v[8:9], off
	s_nop 0
	global_load_dwordx4 v[8:11], v[8:9], off offset:64
	s_nop 0
	global_load_dwordx4 v[12:15], v[16:17], off
	s_nop 0
	global_load_dwordx4 v[16:19], v[16:17], off offset:64
	s_add_u32 s0, s54, 0x200
	s_addc_u32 s1, s55, 0
	s_and_b64 vcc, exec, s[6:7]
	s_cbranch_vccz .LBB0_233
	s_sub_i32 s2, 0, s25
	s_lshl_b64 s[0:1], s[2:3], 16
	s_add_u32 s6, s96, s0
	s_addc_u32 s7, s97, s1
	s_mov_b64 s[0:1], s[54:55]
	s_cbranch_execz .LBB0_234
	s_branch .LBB0_235

.LBB0_241:
	s_waitcnt vmcnt(0)
	s_cmp_lt_i32 s24, 1
	s_mov_b32 s26, 0
	s_cbranch_scc1 .LBB0_289
	v_and_b32_e32 v23, 12, v2
	v_lshrrev_b32_e64 v23, v23, s57
	v_xor_b32_e32 v0, v23, v0
	v_ashrrev_i32_e32 v2, 7, v2
	v_lshlrev_b32_e32 v22, 6, v3
	v_lshlrev_b32_e32 v0, 4, v0
	v_add_u32_e32 v2, s14, v2
	v_and_or_b32 v0, v0, 48, v22
	v_max_i32_e32 v22, 4, v2
	v_add_u32_e32 v22, -4, v22
	v_and_b32_e32 v20, 32, v20
	v_min_u32_e32 v166, 0x78, v22
	v_or_b32_e32 v22, v20, v3
	v_lshlrev_b32_e32 v21, 3, v21
	v_sub_u32_e64 v23, v22, 8 clamp
	v_cmp_ge_u32_e64 s[0:1], v21, v23
	v_add_u32_e32 v24, 16, v23
	v_or_b32_e32 v25, 2, v21
	v_writelane_b32 v224, s0, 26
	v_or_b32_e32 v26, 1, v21
	v_or_b32_e32 v27, 3, v21
	v_writelane_b32 v224, s1, 27
	v_cmp_lt_u32_e64 s[0:1], v21, v24
	v_or_b32_e32 v28, 4, v21
	v_or_b32_e32 v29, 6, v21
	v_writelane_b32 v224, s0, 28
	v_or_b32_e32 v30, 5, v21
	v_or_b32_e32 v31, 7, v21
	v_writelane_b32 v224, s1, 29
	v_cmp_lt_u32_e64 s[0:1], v25, v23
	v_or_b32_e32 v32, 32, v21
	v_or_b32_e32 v33, 34, v21
	v_writelane_b32 v224, s0, 30
	v_or_b32_e32 v34, 33, v21
	v_or_b32_e32 v35, 35, v21
	v_writelane_b32 v224, s1, 31
	v_cmp_lt_u32_e64 s[0:1], v26, v23
	v_or_b32_e32 v36, 36, v21
	v_or_b32_e32 v37, 38, v21
	v_writelane_b32 v224, s0, 32
	v_or_b32_e32 v38, 37, v21
	v_min_u32_e32 v22, 40, v22
	v_writelane_b32 v224, s1, 33
	v_cmp_lt_u32_e64 s[0:1], v25, v24
	v_add_u32_e32 v168, 0, v0
	v_sub_u32_e32 v0, v21, v3
	v_writelane_b32 v224, s0, 34
	s_mul_i32 s2, s21, 0x7c
	v_sub_u32_e32 v0, v0, v20
	v_writelane_b32 v224, s1, 35
	v_cmp_lt_u32_e64 s[0:1], v26, v24
	v_max_i32_e32 v3, -16, v0
	v_add_u32_e32 v3, 16, v3
	v_writelane_b32 v224, s0, 36
	v_min_u32_e32 v3, 30, v3
	v_lshlrev_b32_e32 v169, 2, v3
	v_writelane_b32 v224, s1, 37
	v_cmp_lt_u32_e64 s[0:1], v27, v23
	v_mov_b32_e32 v219, 0
	v_add_u32_e32 v167, 8, v166
	v_writelane_b32 v224, s0, 38
	s_mov_b32 s27, 2
	s_sub_i32 s14, 0, s25
	v_writelane_b32 v224, s1, 39
	v_cmp_lt_u32_e64 s[0:1], v27, v24
	v_mov_b32_e32 v220, 0
	s_mov_b32 s12, 0
	v_writelane_b32 v224, s0, 40
	v_mov_b32_e32 v56, 0
	v_mov_b32_e32 v57, v219
	v_writelane_b32 v224, s1, 41
	v_cmp_ge_u32_e64 s[0:1], v28, v23
	v_mov_b32_e32 v58, v219
	v_mov_b32_e32 v59, v219
	v_writelane_b32 v224, s0, 42
	v_mov_b32_e32 v39, v219
	s_nop 0
	v_writelane_b32 v224, s1, 43
	v_cmp_lt_u32_e64 s[0:1], v28, v24
	s_nop 1
	v_writelane_b32 v224, s0, 44
	s_nop 1
	v_writelane_b32 v224, s1, 45
	v_cmp_lt_u32_e64 s[0:1], v29, v23
	s_nop 1
	v_writelane_b32 v224, s0, 46
	s_nop 1
	v_writelane_b32 v224, s1, 47
	v_cmp_lt_u32_e64 s[0:1], v30, v23
	s_nop 1
	v_writelane_b32 v224, s0, 48
	s_nop 1
	v_writelane_b32 v224, s1, 49
	v_cmp_lt_u32_e64 s[0:1], v29, v24
	s_nop 1
	v_writelane_b32 v224, s0, 50
	s_nop 1
	v_writelane_b32 v224, s1, 51
	v_cmp_lt_u32_e64 s[0:1], v30, v24
	s_nop 1
	v_writelane_b32 v224, s0, 52
	s_nop 1
	v_writelane_b32 v224, s1, 53
	v_cmp_lt_u32_e64 s[0:1], v31, v23
	s_nop 1
	v_writelane_b32 v224, s0, 54
	s_nop 1
	v_writelane_b32 v224, s1, 55
	v_cmp_lt_u32_e64 s[0:1], v31, v24
	s_nop 1
	v_writelane_b32 v224, s0, 56
	s_nop 1
	v_writelane_b32 v224, s1, 57
	v_cmp_ge_u32_e64 s[0:1], v32, v23
	s_nop 1
	v_writelane_b32 v224, s0, 58
	s_nop 1
	v_writelane_b32 v224, s1, 59
	v_cmp_lt_u32_e64 s[0:1], v32, v24
	s_nop 1
	v_writelane_b32 v224, s0, 60
	s_nop 1
	v_writelane_b32 v224, s1, 61
	v_cmp_lt_u32_e64 s[0:1], v33, v23
	s_nop 1
	v_writelane_b32 v224, s0, 62
	s_nop 1
	v_writelane_b32 v224, s1, 63
	v_cmp_lt_u32_e64 s[0:1], v34, v23
	s_nop 1
	v_writelane_b32 v221, s0, 0
	s_nop 1
	v_writelane_b32 v221, s1, 1
	v_cmp_lt_u32_e64 s[0:1], v33, v24
	s_nop 1
	v_writelane_b32 v221, s0, 2
	s_nop 1
	v_writelane_b32 v221, s1, 3
	v_cmp_lt_u32_e64 s[0:1], v34, v24
	s_nop 1
	v_writelane_b32 v221, s0, 4
	s_nop 1
	v_writelane_b32 v221, s1, 5
	v_cmp_lt_u32_e64 s[0:1], v35, v23
	s_nop 1
	v_writelane_b32 v221, s0, 6
	s_nop 1
	v_writelane_b32 v221, s1, 7
	v_cmp_lt_u32_e64 s[0:1], v35, v24
	s_nop 1
	v_writelane_b32 v221, s0, 8
	s_nop 1
	v_writelane_b32 v221, s1, 9
	v_cmp_ge_u32_e64 s[0:1], v36, v23
	s_nop 1
	v_writelane_b32 v221, s0, 10
	s_nop 1
	v_writelane_b32 v221, s1, 11
	v_cmp_lt_u32_e64 s[0:1], v36, v24
	s_nop 1
	v_writelane_b32 v221, s0, 12
	s_nop 1
	v_writelane_b32 v221, s1, 13
	v_cmp_lt_u32_e64 s[0:1], v37, v23
	s_nop 1
	v_writelane_b32 v221, s0, 14
	s_nop 1
	v_writelane_b32 v221, s1, 15
	v_cmp_lt_u32_e64 s[0:1], v38, v23
	v_or_b32_e32 v23, 39, v21
	s_nop 0
	v_writelane_b32 v221, s0, 16
	s_nop 1
	v_writelane_b32 v221, s1, 17
	v_cmp_lt_u32_e64 s[0:1], v37, v24
	s_nop 1
	v_writelane_b32 v221, s0, 18
	s_nop 1
	v_writelane_b32 v221, s1, 19
	v_cmp_lt_u32_e64 s[0:1], v38, v24
	s_nop 1
	v_writelane_b32 v221, s0, 20
	s_nop 1
	v_writelane_b32 v221, s1, 21
	v_cmp_lt_u32_e64 s[0:1], v23, v24
	v_add_u32_e32 v24, 8, v22
	v_add_u32_e32 v22, 24, v22
	v_writelane_b32 v221, s0, 22
	v_cmp_lt_u32_e64 s[6:7], v32, v22
	v_cmp_lt_u32_e64 s[8:9], v36, v22
	v_writelane_b32 v221, s1, 23
	v_cmp_ge_u32_e64 s[0:1], v21, v24
	v_cmp_lt_u32_e64 s[16:17], v30, v22
	v_cmp_lt_u32_e64 s[18:19], v31, v24
	v_writelane_b32 v221, s0, 24
	v_cmp_lt_u32_e64 s[36:37], v31, v22
	v_cmp_lt_u32_e64 s[56:57], v33, v24
	v_writelane_b32 v221, s1, 25
	v_cmp_lt_u32_e64 s[0:1], v21, v22
	v_cmp_lt_u32_e64 s[76:77], v34, v24
	v_cmp_lt_u32_e64 s[88:89], v33, v22
	v_writelane_b32 v221, s0, 26
	v_cmp_lt_u32_e64 s[22:23], v35, v24
	v_cmp_lt_u32_e64 s[40:41], v35, v22
	v_writelane_b32 v221, s1, 27
	v_cmp_lt_u32_e64 s[0:1], v25, v24
	v_cmp_ge_u32_e64 s[38:39], v36, v24
	v_cmp_lt_u32_e64 s[42:43], v37, v24
	v_writelane_b32 v221, s0, 28
	v_cmp_lt_u32_e64 s[44:45], v38, v24
	v_cmp_lt_u32_e64 s[46:47], v37, v22
	v_writelane_b32 v221, s1, 29
	v_cmp_lt_u32_e64 s[0:1], v26, v24
	v_cmp_lt_u32_e64 s[48:49], v38, v22
	v_cmp_lt_u32_e64 s[50:51], v23, v24
	v_writelane_b32 v221, s0, 30
	v_cmp_lt_u32_e64 s[52:53], v23, v22
	v_mov_b32_e32 v36, v219
	v_writelane_b32 v221, s1, 31
	v_cmp_lt_u32_e64 s[0:1], v25, v22
	v_mov_b32_e32 v37, v219
	v_mov_b32_e32 v38, v219
	v_writelane_b32 v221, s0, 32
	s_nop 1
	v_writelane_b32 v221, s1, 33
	v_cmp_lt_u32_e64 s[0:1], v26, v22
	s_nop 1
	v_writelane_b32 v221, s0, 34
	s_nop 1
	v_writelane_b32 v221, s1, 35
	v_cmp_lt_u32_e64 s[0:1], v27, v24
	s_nop 1
	v_writelane_b32 v221, s0, 36
	s_nop 1
	v_writelane_b32 v221, s1, 37
	v_cmp_lt_u32_e64 s[0:1], v27, v22
	s_nop 1
	v_writelane_b32 v221, s0, 38
	s_nop 1
	v_writelane_b32 v221, s1, 39
	v_cmp_ge_u32_e64 s[0:1], v28, v24
	s_nop 1
	v_writelane_b32 v221, s0, 40
	s_nop 1
	v_writelane_b32 v221, s1, 41
	v_cmp_lt_u32_e64 s[0:1], v28, v22
	s_nop 1
	v_writelane_b32 v221, s0, 42
	s_nop 1
	v_writelane_b32 v221, s1, 43
	v_cmp_lt_u32_e64 s[0:1], v29, v24
	s_nop 1
	v_writelane_b32 v221, s0, 44
	s_nop 1
	v_writelane_b32 v221, s1, 45
	v_cmp_lt_u32_e64 s[0:1], v30, v24
	s_nop 1
	v_writelane_b32 v221, s0, 46
	s_nop 1
	v_writelane_b32 v221, s1, 47
	v_cmp_lt_u32_e64 s[0:1], v29, v22
	s_nop 1
	v_writelane_b32 v221, s0, 48
	s_nop 1
	v_writelane_b32 v221, s1, 49
	v_writelane_b32 v221, s6, 50
	v_cmp_ge_u32_e64 s[0:1], v32, v24
	s_nop 0
	v_writelane_b32 v221, s7, 51
	v_writelane_b32 v221, s8, 52
	v_cmp_lt_u32_e64 s[6:7], v34, v22
	s_nop 0
	v_writelane_b32 v221, s9, 53
	s_movk_i32 s8, 0x7c
	v_mul_lo_u32 v2, v2, s8
	v_sub_u32_e32 v2, s2, v2
	v_add_u32_e32 v170, 0, v2
	v_max_i32_e32 v2, 0xffffffef, v0
	v_add_u32_e32 v2, 17, v2
	v_min_u32_e32 v2, 30, v2
	v_lshlrev_b32_e32 v171, 2, v2
	v_max_i32_e32 v2, 0xffffffee, v0
	v_add_u32_e32 v2, 18, v2
	v_min_u32_e32 v2, 30, v2
	v_lshlrev_b32_e32 v172, 2, v2
	v_max_i32_e32 v2, -15, v0
	v_add_u32_e32 v2, 15, v2
	v_min_u32_e32 v2, 30, v2
	v_lshlrev_b32_e32 v173, 2, v2
	v_add_u32_e32 v2, 4, v0
	v_max_i32_e32 v3, -16, v2
	v_add_u32_e32 v3, 16, v3
	v_min_u32_e32 v3, 30, v3
	v_lshlrev_b32_e32 v174, 2, v3
	v_max_i32_e32 v3, 0xffffffef, v2
	v_add_u32_e32 v3, 17, v3
	v_min_u32_e32 v3, 30, v3
	v_lshlrev_b32_e32 v175, 2, v3
	v_max_i32_e32 v3, 0xffffffee, v2
	v_max_i32_e32 v2, -15, v2
	v_add_u32_e32 v2, 15, v2
	v_min_u32_e32 v2, 30, v2
	v_lshlrev_b32_e32 v177, 2, v2
	v_add_u32_e32 v2, 48, v0
	v_min_u32_e32 v2, 30, v2
	v_lshlrev_b32_e32 v178, 2, v2
	v_add_u32_e32 v2, 49, v0
	v_min_u32_e32 v2, 30, v2
	v_lshlrev_b32_e32 v179, 2, v2
	v_add_u32_e32 v2, 50, v0
	v_min_u32_e32 v2, 30, v2
	v_lshlrev_b32_e32 v180, 2, v2
	v_add_u32_e32 v2, 47, v0
	v_min_u32_e32 v2, 30, v2
	v_lshlrev_b32_e32 v181, 2, v2
	v_add_u32_e32 v2, 52, v0
	v_min_u32_e32 v2, 30, v2
	v_lshlrev_b32_e32 v182, 2, v2
	v_add_u32_e32 v2, 53, v0
	v_min_u32_e32 v2, 30, v2
	v_lshlrev_b32_e32 v183, 2, v2
	v_add_u32_e32 v2, 54, v0
	v_min_u32_e32 v2, 30, v2
	v_lshlrev_b32_e32 v184, 2, v2
	v_add_u32_e32 v2, 51, v0
	v_add_u32_e32 v3, 18, v3
	v_min_u32_e32 v2, 30, v2
	v_min_u32_e32 v3, 30, v3
	v_lshlrev_b32_e32 v185, 2, v2
	v_add_u32_e32 v2, -16, v0
	v_lshlrev_b32_e32 v176, 2, v3
	v_max_i32_e32 v3, -16, v2
	v_lshlrev_b32_e32 v186, 2, v3
	v_max_i32_e32 v3, 0xffffffef, v2
	v_lshlrev_b32_e32 v187, 2, v3
	v_max_i32_e32 v3, 0xffffffee, v2
	v_max_i32_e32 v2, -15, v2
	v_lshlrev_b32_e32 v189, 2, v2
	v_add_u32_e32 v2, -12, v0
	v_lshlrev_b32_e32 v188, 2, v3
	v_max_i32_e32 v3, -16, v2
	v_add_u32_e32 v3, 16, v3
	v_min_u32_e32 v3, 30, v3
	v_lshlrev_b32_e32 v190, 2, v3
	v_max_i32_e32 v3, 0xffffffef, v2
	v_add_u32_e32 v3, 17, v3
	v_min_u32_e32 v3, 30, v3
	v_lshlrev_b32_e32 v191, 2, v3
	v_max_i32_e32 v3, 0xffffffee, v2
	v_add_u32_e32 v3, 18, v3
	v_max_i32_e32 v2, -15, v2
	v_min_u32_e32 v3, 30, v3
	v_lshlrev_b32_e32 v193, 2, v2
	v_add_u32_e32 v2, 16, v0
	v_lshlrev_b32_e32 v192, 2, v3
	v_max_i32_e32 v3, -16, v2
	v_add_u32_e32 v3, 16, v3
	v_min_u32_e32 v3, 30, v3
	v_lshlrev_b32_e32 v194, 2, v3
	v_max_i32_e32 v3, 0xffffffef, v2
	v_add_u32_e32 v3, 17, v3
	v_min_u32_e32 v3, 30, v3
	v_lshlrev_b32_e32 v195, 2, v3
	v_max_i32_e32 v3, 0xffffffee, v2
	v_max_i32_e32 v2, -15, v2
	v_add_u32_e32 v2, 15, v2
	v_min_u32_e32 v2, 30, v2
	v_add_u32_e32 v0, 20, v0
	v_lshlrev_b32_e32 v214, 2, v2
	v_max_i32_e32 v2, -16, v0
	v_add_u32_e32 v2, 16, v2
	v_min_u32_e32 v2, 30, v2
	v_lshlrev_b32_e32 v215, 2, v2
	v_max_i32_e32 v2, 0xffffffef, v0
	v_add_u32_e32 v2, 17, v2
	v_min_u32_e32 v2, 30, v2
	v_lshlrev_b32_e32 v216, 2, v2
	v_max_i32_e32 v2, 0xffffffee, v0
	v_add_u32_e32 v3, 18, v3
	v_add_u32_e32 v2, 18, v2
	v_max_i32_e32 v0, -15, v0
	v_min_u32_e32 v3, 30, v3
	v_min_u32_e32 v2, 30, v2
	v_add_u32_e32 v0, 15, v0
	v_lshlrev_b32_e32 v213, 2, v3
	v_lshlrev_b32_e32 v217, 2, v2
	v_min_u32_e32 v0, 30, v0
	v_mov_b32_e32 v2, v1
	v_mov_b32_e32 v3, v1
	v_lshlrev_b32_e32 v218, 2, v0
	v_mov_b32_e32 v0, v1
	v_mov_b64_e32 v[54:55], v[2:3]
	v_mov_b64_e32 v[34:35], v[2:3]
	v_mov_b64_e32 v[50:51], v[2:3]
	v_mov_b64_e32 v[30:31], v[2:3]
	v_mov_b64_e32 v[46:47], v[2:3]
	v_mov_b64_e32 v[26:27], v[2:3]
	v_mov_b64_e32 v[42:43], v[2:3]
	v_mov_b64_e32 v[22:23], v[2:3]
	s_mov_b64 s[8:9], -1
	v_mov_b64_e32 v[52:53], v[0:1]
	v_mov_b64_e32 v[32:33], v[0:1]
	v_mov_b64_e32 v[48:49], v[0:1]
	v_mov_b64_e32 v[28:29], v[0:1]
	v_mov_b64_e32 v[44:45], v[0:1]
	v_mov_b64_e32 v[24:25], v[0:1]
	v_mov_b64_e32 v[40:41], v[0:1]
	v_mov_b64_e32 v[20:21], v[0:1]
	v_readlane_b32 vcc_lo, v225, 56
	v_readlane_b32 s100, v225, 16
	v_readlane_b32 s101, v225, 17
	s_nop 3
	s_cmp_ge_u32 vcc_lo, 12
	s_cselect_b32 vcc_lo, 8, 0
	s_and_b32 vcc_hi, s20, 7
	s_add_i32 vcc_lo, vcc_lo, vcc_hi
	s_mulk_i32 vcc_lo, 0x744
	s_add_u32 s100, s100, vcc_lo
	s_addc_u32 s101, s101, 0
	v_and_b32_e32 v124, 31, v196
	v_lshrrev_b32_e32 v125, 5, v196
	v_mul_u32_u24_e32 v126, 31, v125
	v_add_u32_e32 v126, v126, v124
	v_lshlrev_b32_e32 v126, 2, v126
	v_add_u32_e32 v128, 0x3e0, v126
	v_min_u32_e32 v126, 0x740, v126
	v_min_u32_e32 v128, 0x740, v128
	global_load_dword v127, v126, s[100:101]
	global_load_dword v129, v128, s[100:101]
	v_and_b32_e32 v130, 15, v196
	v_bfe_u32 v131, v196, 4, 2
	v_lshrrev_b32_e32 v132, 6, v196
	v_and_b32_e32 v133, 1, v132
	v_lshl_add_u32 v133, v133, 5, v130
	v_lshlrev_b32_e32 v131, 3, v131
	s_bfe_u32 vcc_lo, s20, 0x60003
	s_lshl_b32 vcc_lo, vcc_lo, 1
	v_lshrrev_b32_e32 v218, 1, v132
	v_add_u32_e32 v218, vcc_lo, v218
	v_mov_b32_e32 v137, 0x7c
	v_add_u32_e32 v134, -8, v133
	v_max_i32_e32 v134, 0, v134
	v_min_i32_e32 v134, 48, v134
	v_add_u32_e32 v135, 0, v131
	v_sub_u32_e32 v136, v135, v134
	v_cmp_gt_u32_e32 vcc, 16, v136
	v_sub_u32_e32 v135, v135, v133
	v_add_u32_e32 v135, 15, v135
	v_lshlrev_b32_e32 v135, 2, v135
	v_cndmask_b32_e32 v169, v137, v135, vcc
	v_add_u32_e32 v135, 1, v131
	v_sub_u32_e32 v136, v135, v134
	v_cmp_gt_u32_e32 vcc, 16, v136
	v_sub_u32_e32 v135, v135, v133
	v_add_u32_e32 v135, 15, v135
	v_lshlrev_b32_e32 v135, 2, v135
	v_cndmask_b32_e32 v171, v137, v135, vcc
	v_add_u32_e32 v135, 2, v131
	v_sub_u32_e32 v136, v135, v134
	v_cmp_gt_u32_e32 vcc, 16, v136
	v_sub_u32_e32 v135, v135, v133
	v_add_u32_e32 v135, 15, v135
	v_lshlrev_b32_e32 v135, 2, v135
	v_cndmask_b32_e32 v172, v137, v135, vcc
	v_add_u32_e32 v135, 3, v131
	v_sub_u32_e32 v136, v135, v134
	v_cmp_gt_u32_e32 vcc, 16, v136
	v_sub_u32_e32 v135, v135, v133
	v_add_u32_e32 v135, 15, v135
	v_lshlrev_b32_e32 v135, 2, v135
	v_cndmask_b32_e32 v173, v137, v135, vcc
	v_add_u32_e32 v135, 4, v131
	v_sub_u32_e32 v136, v135, v134
	v_cmp_gt_u32_e32 vcc, 16, v136
	v_sub_u32_e32 v135, v135, v133
	v_add_u32_e32 v135, 15, v135
	v_lshlrev_b32_e32 v135, 2, v135
	v_cndmask_b32_e32 v174, v137, v135, vcc
	v_add_u32_e32 v135, 5, v131
	v_sub_u32_e32 v136, v135, v134
	v_cmp_gt_u32_e32 vcc, 16, v136
	v_sub_u32_e32 v135, v135, v133
	v_add_u32_e32 v135, 15, v135
	v_lshlrev_b32_e32 v135, 2, v135
	v_cndmask_b32_e32 v175, v137, v135, vcc
	v_add_u32_e32 v135, 6, v131
	v_sub_u32_e32 v136, v135, v134
	v_cmp_gt_u32_e32 vcc, 16, v136
	v_sub_u32_e32 v135, v135, v133
	v_add_u32_e32 v135, 15, v135
	v_lshlrev_b32_e32 v135, 2, v135
	v_cndmask_b32_e32 v176, v137, v135, vcc
	v_add_u32_e32 v135, 7, v131
	v_sub_u32_e32 v136, v135, v134
	v_cmp_gt_u32_e32 vcc, 16, v136
	v_sub_u32_e32 v135, v135, v133
	v_add_u32_e32 v135, 15, v135
	v_lshlrev_b32_e32 v135, 2, v135
	v_cndmask_b32_e32 v177, v137, v135, vcc
	v_add_u32_e32 v135, 32, v131
	v_sub_u32_e32 v136, v135, v134
	v_cmp_gt_u32_e32 vcc, 16, v136
	v_sub_u32_e32 v135, v135, v133
	v_add_u32_e32 v135, 15, v135
	v_lshlrev_b32_e32 v135, 2, v135
	v_cndmask_b32_e32 v178, v137, v135, vcc
	v_add_u32_e32 v135, 33, v131
	v_sub_u32_e32 v136, v135, v134
	v_cmp_gt_u32_e32 vcc, 16, v136
	v_sub_u32_e32 v135, v135, v133
	v_add_u32_e32 v135, 15, v135
	v_lshlrev_b32_e32 v135, 2, v135
	v_cndmask_b32_e32 v179, v137, v135, vcc
	v_add_u32_e32 v135, 34, v131
	v_sub_u32_e32 v136, v135, v134
	v_cmp_gt_u32_e32 vcc, 16, v136
	v_sub_u32_e32 v135, v135, v133
	v_add_u32_e32 v135, 15, v135
	v_lshlrev_b32_e32 v135, 2, v135
	v_cndmask_b32_e32 v180, v137, v135, vcc
	v_add_u32_e32 v135, 35, v131
	v_sub_u32_e32 v136, v135, v134
	v_cmp_gt_u32_e32 vcc, 16, v136
	v_sub_u32_e32 v135, v135, v133
	v_add_u32_e32 v135, 15, v135
	v_lshlrev_b32_e32 v135, 2, v135
	v_cndmask_b32_e32 v181, v137, v135, vcc
	v_add_u32_e32 v135, 36, v131
	v_sub_u32_e32 v136, v135, v134
	v_cmp_gt_u32_e32 vcc, 16, v136
	v_sub_u32_e32 v135, v135, v133
	v_add_u32_e32 v135, 15, v135
	v_lshlrev_b32_e32 v135, 2, v135
	v_cndmask_b32_e32 v182, v137, v135, vcc
	v_add_u32_e32 v135, 37, v131
	v_sub_u32_e32 v136, v135, v134
	v_cmp_gt_u32_e32 vcc, 16, v136
	v_sub_u32_e32 v135, v135, v133
	v_add_u32_e32 v135, 15, v135
	v_lshlrev_b32_e32 v135, 2, v135
	v_cndmask_b32_e32 v183, v137, v135, vcc
	v_add_u32_e32 v135, 38, v131
	v_sub_u32_e32 v136, v135, v134
	v_cmp_gt_u32_e32 vcc, 16, v136
	v_sub_u32_e32 v135, v135, v133
	v_add_u32_e32 v135, 15, v135
	v_lshlrev_b32_e32 v135, 2, v135
	v_cndmask_b32_e32 v184, v137, v135, vcc
	v_add_u32_e32 v135, 39, v131
	v_sub_u32_e32 v136, v135, v134
	v_cmp_gt_u32_e32 vcc, 16, v136
	v_sub_u32_e32 v135, v135, v133
	v_add_u32_e32 v135, 15, v135
	v_lshlrev_b32_e32 v135, 2, v135
	v_cndmask_b32_e32 v185, v137, v135, vcc
	v_add_u32_e32 v133, 16, v133
	v_add_u32_e32 v134, -8, v133
	v_max_i32_e32 v134, 0, v134
	v_min_i32_e32 v134, 48, v134
	v_add_u32_e32 v135, 0, v131
	v_sub_u32_e32 v136, v135, v134
	v_cmp_gt_u32_e32 vcc, 16, v136
	v_sub_u32_e32 v135, v135, v133
	v_add_u32_e32 v135, 15, v135
	v_lshlrev_b32_e32 v135, 2, v135
	v_cndmask_b32_e32 v186, v137, v135, vcc
	v_add_u32_e32 v135, 1, v131
	v_sub_u32_e32 v136, v135, v134
	v_cmp_gt_u32_e32 vcc, 16, v136
	v_sub_u32_e32 v135, v135, v133
	v_add_u32_e32 v135, 15, v135
	v_lshlrev_b32_e32 v135, 2, v135
	v_cndmask_b32_e32 v187, v137, v135, vcc
	v_add_u32_e32 v135, 2, v131
	v_sub_u32_e32 v136, v135, v134
	v_cmp_gt_u32_e32 vcc, 16, v136
	v_sub_u32_e32 v135, v135, v133
	v_add_u32_e32 v135, 15, v135
	v_lshlrev_b32_e32 v135, 2, v135
	v_cndmask_b32_e32 v188, v137, v135, vcc
	v_add_u32_e32 v135, 3, v131
	v_sub_u32_e32 v136, v135, v134
	v_cmp_gt_u32_e32 vcc, 16, v136
	v_sub_u32_e32 v135, v135, v133
	v_add_u32_e32 v135, 15, v135
	v_lshlrev_b32_e32 v135, 2, v135
	v_cndmask_b32_e32 v189, v137, v135, vcc
	v_add_u32_e32 v135, 4, v131
	v_sub_u32_e32 v136, v135, v134
	v_cmp_gt_u32_e32 vcc, 16, v136
	v_sub_u32_e32 v135, v135, v133
	v_add_u32_e32 v135, 15, v135
	v_lshlrev_b32_e32 v135, 2, v135
	v_cndmask_b32_e32 v190, v137, v135, vcc
	v_add_u32_e32 v135, 5, v131
	v_sub_u32_e32 v136, v135, v134
	v_cmp_gt_u32_e32 vcc, 16, v136
	v_sub_u32_e32 v135, v135, v133
	v_add_u32_e32 v135, 15, v135
	v_lshlrev_b32_e32 v135, 2, v135
	v_cndmask_b32_e32 v191, v137, v135, vcc
	v_add_u32_e32 v135, 6, v131
	v_sub_u32_e32 v136, v135, v134
	v_cmp_gt_u32_e32 vcc, 16, v136
	v_sub_u32_e32 v135, v135, v133
	v_add_u32_e32 v135, 15, v135
	v_lshlrev_b32_e32 v135, 2, v135
	v_cndmask_b32_e32 v192, v137, v135, vcc
	v_add_u32_e32 v135, 7, v131
	v_sub_u32_e32 v136, v135, v134
	v_cmp_gt_u32_e32 vcc, 16, v136
	v_sub_u32_e32 v135, v135, v133
	v_add_u32_e32 v135, 15, v135
	v_lshlrev_b32_e32 v135, 2, v135
	v_cndmask_b32_e32 v193, v137, v135, vcc
	v_add_u32_e32 v135, 32, v131
	v_sub_u32_e32 v136, v135, v134
	v_cmp_gt_u32_e32 vcc, 16, v136
	v_sub_u32_e32 v135, v135, v133
	v_add_u32_e32 v135, 15, v135
	v_lshlrev_b32_e32 v135, 2, v135
	v_cndmask_b32_e32 v194, v137, v135, vcc
	v_add_u32_e32 v135, 33, v131
	v_sub_u32_e32 v136, v135, v134
	v_cmp_gt_u32_e32 vcc, 16, v136
	v_sub_u32_e32 v135, v135, v133
	v_add_u32_e32 v135, 15, v135
	v_lshlrev_b32_e32 v135, 2, v135
	v_cndmask_b32_e32 v195, v137, v135, vcc
	v_add_u32_e32 v135, 34, v131
	v_sub_u32_e32 v136, v135, v134
	v_cmp_gt_u32_e32 vcc, 16, v136
	v_sub_u32_e32 v135, v135, v133
	v_add_u32_e32 v135, 15, v135
	v_lshlrev_b32_e32 v135, 2, v135
	v_cndmask_b32_e32 v213, v137, v135, vcc
	v_add_u32_e32 v135, 35, v131
	v_sub_u32_e32 v136, v135, v134
	v_cmp_gt_u32_e32 vcc, 16, v136
	v_sub_u32_e32 v135, v135, v133
	v_add_u32_e32 v135, 15, v135
	v_lshlrev_b32_e32 v135, 2, v135
	v_cndmask_b32_e32 v214, v137, v135, vcc
	v_add_u32_e32 v135, 36, v131
	v_sub_u32_e32 v136, v135, v134
	v_cmp_gt_u32_e32 vcc, 16, v136
	v_sub_u32_e32 v135, v135, v133
	v_add_u32_e32 v135, 15, v135
	v_lshlrev_b32_e32 v135, 2, v135
	v_cndmask_b32_e32 v215, v137, v135, vcc
	v_add_u32_e32 v135, 37, v131
	v_sub_u32_e32 v136, v135, v134
	v_cmp_gt_u32_e32 vcc, 16, v136
	v_sub_u32_e32 v135, v135, v133
	v_add_u32_e32 v135, 15, v135
	v_lshlrev_b32_e32 v135, 2, v135
	v_cndmask_b32_e32 v216, v137, v135, vcc
	v_add_u32_e32 v135, 38, v131
	v_sub_u32_e32 v136, v135, v134
	v_cmp_gt_u32_e32 vcc, 16, v136
	v_sub_u32_e32 v135, v135, v133
	v_add_u32_e32 v135, 15, v135
	v_lshlrev_b32_e32 v135, 2, v135
	v_cndmask_b32_e32 v217, v137, v135, vcc
	v_add_u32_e32 v135, 39, v131
	v_sub_u32_e32 v136, v135, v134
	v_cmp_gt_u32_e32 vcc, 16, v136
	v_sub_u32_e32 v135, v135, v133
	v_add_u32_e32 v135, 15, v135
	v_lshlrev_b32_e32 v135, 2, v135
	v_cndmask_b32_e32 v170, v137, v135, vcc
	s_waitcnt vmcnt(0)
	v_mul_f32_e32 v127, 0x3fb8aa3b, v127
	v_mul_f32_e32 v129, 0x3fb8aa3b, v129
	v_cmp_gt_u32_e32 vcc, 31, v124
	v_lshlrev_b32_e32 v130, 2, v196
	s_nop 1
	v_cndmask_b32_e32 v127, v205, v127, vcc
	v_cndmask_b32_e32 v129, v205, v129, vcc
	ds_write_b32 v130, v127 offset:51200
	ds_write_b32 v130, v129 offset:52224
	s_add_i32 s15, s12, 1
	s_cmp_ge_i32 s15, s24
	s_mov_b64 s[10:11], -1
	s_cbranch_scc0 .LBB0_244

.LBB0_293:
	s_andn2_b64 vcc, exec, s[94:95]
	s_mov_b64 s[94:95], s[8:9]
	s_cbranch_vccnz .LBB0_208
	v_mov_b32_e32 v100, v196
	s_movk_i32 s13, 0xffe0
	v_and_b32_e32 v6, 15, v100
	v_bfe_u32 v8, v100, 4, 2
	v_ashrrev_i32_e32 v0, 1, v100
	v_and_or_b32 v132, v0, s13, v6
	v_lshlrev_b32_e32 v0, 4, v8
	v_lshl_add_u64 v[2:3], s[90:91], 0, v[0:1]
	s_movk_i32 s12, 0x600
	v_mad_i64_i32 v[4:5], s[10:11], v132, s12, v[2:3]
	global_load_dwordx4 v[46:49], v[4:5], off
	global_load_dwordx4 v[42:45], v[4:5], off offset:64
	v_or_b32_e32 v130, 16, v132
	v_mad_i64_i32 v[2:3], s[10:11], v130, s12, v[2:3]
	global_load_dwordx4 v[50:53], v[4:5], off offset:128
	global_load_dwordx4 v[62:65], v[2:3], off
	global_load_dwordx4 v[58:61], v[2:3], off offset:64
	global_load_dwordx4 v[54:57], v[2:3], off offset:128
	v_lshrrev_b32_e32 v2, 1, v100
	v_lshrrev_b32_e32 v7, 4, v100
	v_ashrrev_i32_e32 v101, 2, v100
	v_and_b32_e32 v2, 24, v2
	v_lshlrev_b32_e32 v140, 2, v8
	v_and_or_b32 v2, v101, s13, v2
	v_and_b32_e32 v3, 4, v7
	v_and_b32_e32 v5, 3, v101
	v_lshrrev_b32_e64 v0, v140, s57
	v_or3_b32 v102, v2, v3, v5
	s_movk_i32 s10, 0x60
	v_xor_b32_e32 v4, v0, v100
	v_mad_i64_i32 v[2:3], s[10:11], v102, s10, 0
	s_mul_i32 s0, s93, 0x18c000
	s_mul_hi_u32 s4, s92, 0x18c000
	v_lshlrev_b32_e32 v4, 3, v4
	s_movk_i32 s10, 0x2100
	s_add_i32 s4, s4, s0
	s_mul_i32 s5, s92, 0x18c000
	v_readlane_b32 s0, v224, 7
	v_and_b32_e32 v8, 24, v4
	v_mad_i64_i32 v[4:5], s[10:11], v101, s10, 0
	s_add_u32 s0, s0, s5
	v_readlane_b32 s1, v224, 8
	v_or_b32_e32 v2, v2, v8
	v_or_b32_e32 v4, v4, v8
	v_and_b32_e32 v8, 12, v100
	s_addc_u32 s1, s1, s4
	v_lshl_add_u32 v142, v100, 4, 0
	v_lshrrev_b32_e64 v8, v8, s57
	v_xor_b32_e32 v7, v8, v7
	v_lshl_add_u64 v[2:3], v[2:3], 1, s[0:1]
	v_readfirstlane_b32 s0, v142
	v_add_u32_e32 v8, 0x1000, v142
	v_lshlrev_b32_e32 v6, 6, v6
	v_lshlrev_b32_e32 v7, 4, v7
	s_mov_b32 m0, s0
	v_readfirstlane_b32 s0, v8
	v_add_u32_e32 v8, 0x2000, v142
	s_mul_i32 s6, s93, 0x108000
	s_mul_hi_u32 s7, s92, 0x108000
	v_and_or_b32 v141, v7, 48, v6
	global_load_lds_dwordx4 v[2:3], off
	v_lshl_add_u64 v[6:7], v[2:3], 0, 64
	s_mov_b32 m0, s0
	v_readfirstlane_b32 s0, v8
	s_add_i32 s6, s7, s6
	s_mul_i32 s7, s92, 0x108000
	v_readlane_b32 s8, v224, 9
	global_load_lds_dwordx4 v[6:7], off
	v_lshl_add_u64 v[6:7], v[2:3], 0, s[78:79]
	s_mov_b32 m0, s0
	s_add_u32 s8, s8, s7
	v_readlane_b32 s9, v224, 10
	global_load_lds_dwordx4 v[6:7], off
	v_add_u32_e32 v6, 0x3000, v142
	s_addc_u32 s9, s9, s6
	v_readfirstlane_b32 s0, v6
	v_add_u32_e32 v8, 0x4000, v142
	v_lshl_add_u64 v[4:5], v[4:5], 1, s[8:9]
	s_mov_b32 m0, s0
	v_readfirstlane_b32 s0, v8
	v_add_u32_e32 v8, 0x5000, v142
	global_load_lds_dwordx4 v[4:5], off
	v_lshl_add_u64 v[6:7], v[4:5], 0, 64
	s_mov_b32 m0, s0
	v_readfirstlane_b32 s0, v8
	global_load_lds_dwordx4 v[6:7], off
	v_lshl_add_u64 v[6:7], v[2:3], 0, s[24:25]
	s_mov_b32 m0, s0
	s_mov_b64 s[0:1], 0x3040
	v_add_u32_e32 v8, 0x6000, v142
	global_load_lds_dwordx4 v[6:7], off
	v_lshl_add_u64 v[6:7], v[2:3], 0, s[0:1]
	v_readfirstlane_b32 s0, v8
	s_mov_b32 m0, s0
	s_mov_b64 s[0:1], 0x3080
	v_add_u32_e32 v8, 0x7000, v142
	global_load_lds_dwordx4 v[6:7], off
	v_lshl_add_u64 v[6:7], v[2:3], 0, s[0:1]
	v_readfirstlane_b32 s0, v8
	v_add_u32_e32 v8, 0x8000, v142
	s_mov_b32 m0, s0
	v_readfirstlane_b32 s0, v8
	v_add_u32_e32 v8, 0x9000, v142
	global_load_lds_dwordx4 v[6:7], off
	v_lshl_add_u64 v[6:7], v[4:5], 0, s[78:79]
	s_mov_b32 m0, s0
	v_readfirstlane_b32 s0, v8
	global_load_lds_dwordx4 v[6:7], off
	v_lshl_add_u64 v[6:7], v[4:5], 0, s[84:85]
	s_mov_b32 m0, s0
	v_add_u32_e32 v8, 0xa000, v142
	s_mov_b64 s[0:1], 0x6000
	global_load_lds_dwordx4 v[6:7], off
	v_lshl_add_u64 v[6:7], v[2:3], 0, s[0:1]
	v_readfirstlane_b32 s0, v8
	s_waitcnt vmcnt(5) lgkmcnt(0)
	s_barrier
	s_mov_b32 m0, s0
	s_mov_b64 s[0:1], 0x6040
	v_add_u32_e32 v8, 0xb000, v142
	global_load_lds_dwordx4 v[6:7], off
	v_lshl_add_u64 v[6:7], v[2:3], 0, s[0:1]
	v_readfirstlane_b32 s0, v8
	s_mov_b32 m0, s0
	s_mov_b64 s[0:1], 0x6080
	global_load_lds_dwordx4 v[6:7], off
	v_add_u32_e32 v6, 0xc000, v142
	v_lshl_add_u64 v[2:3], v[2:3], 0, s[0:1]
	v_readfirstlane_b32 s0, v6
	s_mov_b32 m0, s0
	s_mov_b64 s[0:1], 0x100
	v_add_u32_e32 v6, 0xd000, v142
	global_load_lds_dwordx4 v[2:3], off
	v_lshl_add_u64 v[2:3], v[4:5], 0, s[0:1]
	v_readfirstlane_b32 s0, v6
	s_mov_b32 m0, s0
	s_mov_b64 s[0:1], 0x140
	global_load_lds_dwordx4 v[2:3], off
	v_lshl_add_u64 v[2:3], v[4:5], 0, s[0:1]
	v_add_u32_e32 v4, 0xe000, v142
	v_add_u32_e32 v143, 0, v141
	v_readfirstlane_b32 s0, v4
	s_mov_b32 m0, s0
	s_mov_b32 s81, s80
	global_load_lds_dwordx4 v[2:3], off
	ds_read_b128 v[2:5], v143
	ds_read_b128 v[6:9], v143 offset:1024
	s_waitcnt lgkmcnt(0)
	v_mfma_f32_16x16x32_bf16 v[10:13], v[2:5], v[46:49], 0
	ds_read_b128 v[14:17], v143 offset:4096
	ds_read_b128 v[18:21], v143 offset:5120
	s_mov_b32 s82, s80
	s_mov_b32 s83, s80
	v_mfma_f32_16x16x32_bf16 v[2:5], v[2:5], v[62:65], 0
	s_add_u32 s8, s22, s5
	s_addc_u32 s9, s23, s4
	v_bitop3_b32 v0, v0, 3, v100 bitop3:0x48
	s_waitcnt lgkmcnt(1)
	v_mfma_f32_16x16x32_bf16 v[10:13], v[14:17], v[42:45], v[10:13]
	s_mov_b32 s0, 1
	v_ashrrev_i32_e32 v133, 31, v132
	v_ashrrev_i32_e32 v131, 31, v130
	v_mfma_f32_16x16x32_bf16 v[2:5], v[14:17], v[58:61], v[2:5]
	ds_read_b128 v[14:17], v143 offset:8192
	ds_read_b128 v[22:25], v143 offset:9216
	s_mov_b32 s1, 2
	v_lshlrev_b32_e32 v0, 4, v0
	s_waitcnt lgkmcnt(1)
	v_mfma_f32_16x16x32_bf16 v[10:13], v[14:17], v[50:53], v[10:13]
	v_mfma_f32_16x16x32_bf16 v[2:5], v[14:17], v[54:57], v[2:5]
	v_mfma_f32_16x16x32_bf16 v[14:17], v[6:9], v[46:49], 0
	v_mfma_f32_16x16x32_bf16 v[6:9], v[6:9], v[62:65], 0
	v_mfma_f32_16x16x32_bf16 v[14:17], v[18:21], v[42:45], v[14:17]
	v_mfma_f32_16x16x32_bf16 v[6:9], v[18:21], v[58:61], v[6:9]
	s_waitcnt lgkmcnt(0)
	v_mfma_f32_16x16x32_bf16 v[14:17], v[22:25], v[50:53], v[14:17]
	v_mfma_f32_16x16x32_bf16 v[6:9], v[22:25], v[54:57], v[6:9]
	ds_read_b128 v[18:21], v143 offset:2048
	ds_read_b128 v[22:25], v143 offset:3072
	ds_read_b128 v[30:33], v143 offset:6144
	ds_read_b128 v[34:37], v143 offset:7168
	s_waitcnt lgkmcnt(3)
	v_mfma_f32_16x16x32_bf16 v[26:29], v[18:21], v[46:49], 0
	v_mfma_f32_16x16x32_bf16 v[18:21], v[18:21], v[62:65], 0
	s_waitcnt lgkmcnt(1)
	v_mfma_f32_16x16x32_bf16 v[26:29], v[30:33], v[42:45], v[26:29]
	v_mfma_f32_16x16x32_bf16 v[18:21], v[30:33], v[58:61], v[18:21]
	ds_read_b128 v[30:33], v143 offset:10240
	ds_read_b128 v[38:41], v143 offset:11264
	s_waitcnt lgkmcnt(1)
	v_mfma_f32_16x16x32_bf16 v[26:29], v[30:33], v[50:53], v[26:29]
	v_mfma_f32_16x16x32_bf16 v[18:21], v[30:33], v[54:57], v[18:21]
	v_mfma_f32_16x16x32_bf16 v[30:33], v[22:25], v[46:49], 0
	v_mfma_f32_16x16x32_bf16 v[22:25], v[22:25], v[62:65], 0
	v_mfma_f32_16x16x32_bf16 v[30:33], v[34:37], v[42:45], v[30:33]
	v_mfma_f32_16x16x32_bf16 v[22:25], v[34:37], v[58:61], v[22:25]
	v_max_f32_e32 v34, v11, v11
	v_max_f32_e32 v35, v10, v10
	v_max_f32_e32 v34, v35, v34
	v_max3_f32 v34, v34, v12, v13
	s_waitcnt lgkmcnt(0)
	v_mfma_f32_16x16x32_bf16 v[30:33], v[38:41], v[50:53], v[30:33]
	v_max3_f32 v34, v34, v14, v15
	v_max3_f32 v34, v34, v16, v17
	v_max3_f32 v34, v34, v26, v27
	v_max3_f32 v34, v34, v28, v29
	v_mfma_f32_16x16x32_bf16 v[22:25], v[38:41], v[54:57], v[22:25]
	s_nop 2
	v_max3_f32 v34, v34, v30, v31
	v_max3_f32 v34, v34, v32, v33
	v_mov_b32_e32 v35, v34
	s_nop 1
	v_permlane32_swap_b32_e32 v34, v35
	v_max_f32_e32 v35, v35, v35
	v_max_f32_e32 v34, v34, v34
	v_max_f32_e32 v34, v34, v35
	v_mov_b32_e32 v35, v34
	s_nop 1
	v_permlane16_swap_b32_e32 v34, v35
	v_max_f32_e32 v35, v35, v35
	v_max_f32_e32 v34, v34, v34
	v_max_f32_e32 v98, v34, v35
	v_sub_f32_e32 v11, v11, v98
	v_sub_f32_e32 v10, v10, v98
	v_exp_f32_e32 v10, v10
	v_exp_f32_e32 v11, v11
	v_sub_f32_e32 v27, v27, v98
	v_sub_f32_e32 v26, v26, v98
	v_sub_f32_e32 v17, v17, v98
	v_cvt_pk_bf16_f32 v78, v10, v11
	v_exp_f32_e32 v10, v26
	v_exp_f32_e32 v11, v27
	v_sub_f32_e32 v16, v16, v98
	v_sub_f32_e32 v13, v13, v98
	v_sub_f32_e32 v12, v12, v98
	v_cvt_pk_bf16_f32 v82, v10, v11
	v_max_f32_e32 v10, v3, v3
	v_max_f32_e32 v11, v2, v2
	v_max_f32_e32 v10, v11, v10
	v_max3_f32 v10, v10, v4, v5
	v_max3_f32 v10, v10, v6, v7
	v_max3_f32 v10, v10, v8, v9
	v_max3_f32 v10, v10, v18, v19
	v_max3_f32 v10, v10, v20, v21
	v_max3_f32 v10, v10, v22, v23
	v_max3_f32 v10, v10, v24, v25
	v_mov_b32_e32 v11, v10
	s_nop 1
	v_permlane32_swap_b32_e32 v10, v11
	v_max_f32_e32 v11, v11, v11
	v_max_f32_e32 v10, v10, v10
	v_exp_f32_e32 v16, v16
	v_exp_f32_e32 v17, v17
	v_max_f32_e32 v10, v10, v11
	v_exp_f32_e32 v12, v12
	v_exp_f32_e32 v13, v13
	v_mov_b32_e32 v11, v10
	s_nop 1
	v_permlane16_swap_b32_e32 v10, v11
	v_sub_f32_e32 v33, v33, v98
	v_sub_f32_e32 v32, v32, v98
	v_sub_f32_e32 v15, v15, v98
	v_sub_f32_e32 v14, v14, v98
	v_max_f32_e32 v11, v11, v11
	v_max_f32_e32 v10, v10, v10
	v_sub_f32_e32 v29, v29, v98
	v_sub_f32_e32 v28, v28, v98
	v_exp_f32_e32 v14, v14
	v_exp_f32_e32 v15, v15
	v_cvt_pk_bf16_f32 v81, v16, v17
	v_exp_f32_e32 v16, v32
	v_exp_f32_e32 v17, v33
	v_max_f32_e32 v99, v10, v11
	v_cvt_pk_bf16_f32 v79, v12, v13
	v_exp_f32_e32 v12, v28
	v_exp_f32_e32 v13, v29
	v_sub_f32_e32 v7, v7, v99
	v_sub_f32_e32 v6, v6, v99
	v_exp_f32_e32 v6, v6
	v_exp_f32_e32 v7, v7
	v_sub_f32_e32 v31, v31, v98
	v_sub_f32_e32 v30, v30, v98
	v_exp_f32_e64 v74, -v98
	v_cvt_pk_bf16_f32 v80, v14, v15
	v_exp_f32_e32 v14, v30
	v_exp_f32_e32 v15, v31
	v_cvt_pk_bf16_f32 v85, v16, v17
	v_sub_f32_e32 v17, v18, v99
	v_sub_f32_e32 v9, v9, v99
	v_sub_f32_e32 v8, v8, v99
	v_sub_f32_e32 v5, v5, v99
	v_exp_f32_e64 v18, -v99
	v_sub_f32_e32 v4, v4, v99
	v_sub_f32_e32 v3, v3, v99
	v_sub_f32_e32 v2, v2, v99
	v_cvt_pk_bf16_f32 v83, v12, v13
	v_sub_f32_e32 v10, v25, v99
	v_sub_f32_e32 v11, v24, v99
	v_sub_f32_e32 v12, v23, v99
	v_sub_f32_e32 v13, v22, v99
	v_sub_f32_e32 v16, v19, v99
	v_exp_f32_e32 v2, v2
	v_exp_f32_e32 v3, v3
	v_exp_f32_e32 v4, v4
	v_exp_f32_e32 v5, v5
	v_exp_f32_e32 v8, v8
	v_exp_f32_e32 v9, v9
	v_cvt_pk_bf16_f32 v92, v6, v7
	v_exp_f32_e32 v6, v17
	v_exp_f32_e32 v7, v16
	v_exp_f32_e32 v13, v13
	v_exp_f32_e32 v12, v12
	v_exp_f32_e32 v11, v11
	v_exp_f32_e32 v10, v10
	ds_read_b128 v[34:37], v143 offset:12288
	ds_read_b128 v[38:41], v143 offset:13312
	ds_read_b128 v[66:69], v143 offset:16384
	ds_read_b128 v[70:73], v143 offset:17408
	v_mul_f32_e32 v74, 0, v74
	v_cvt_pk_bf16_f32 v84, v14, v15
	v_sub_f32_e32 v14, v21, v99
	v_sub_f32_e32 v15, v20, v99
	v_mul_f32_e32 v86, 0, v18
	v_mov_b32_e32 v75, v74
	v_mov_b32_e32 v76, v74
	v_mov_b32_e32 v77, v74
	v_mov_b32_e32 v87, v86
	v_mov_b32_e32 v88, v86
	v_mov_b32_e32 v89, v86
	v_cvt_pk_bf16_f32 v90, v2, v3
	v_cvt_pk_bf16_f32 v91, v4, v5
	v_cvt_pk_bf16_f32 v93, v8, v9
	v_exp_f32_e32 v15, v15
	v_exp_f32_e32 v14, v14
	s_waitcnt lgkmcnt(3)
	v_mfma_f32_16x16x32_bf16 v[2:5], v[34:37], v[78:81], v[74:77]
	v_cvt_pk_bf16_f32 v94, v6, v7
	v_cvt_pk_bf16_f32 v96, v13, v12
	v_cvt_pk_bf16_f32 v97, v11, v10
	v_mfma_f32_16x16x32_bf16 v[6:9], v[34:37], v[90:93], v[86:89]
	ds_read_b128 v[10:13], v143 offset:14336
	ds_read_b128 v[18:21], v143 offset:15360
	v_cvt_pk_bf16_f32 v95, v15, v14
	v_pk_add_f32 v[134:135], v[98:99], 0 op_sel_hi:[1,0]
	s_waitcnt lgkmcnt(3)
	v_mfma_f32_16x16x32_bf16 v[26:29], v[66:69], v[82:85], v[2:5]
	v_mfma_f32_16x16x32_bf16 v[30:33], v[66:69], v[94:97], v[6:9]
	v_mfma_f32_16x16x32_bf16 v[2:5], v[38:41], v[78:81], v[74:77]
	v_mfma_f32_16x16x32_bf16 v[6:9], v[38:41], v[90:93], v[86:89]
	ds_read_b128 v[34:37], v143 offset:18432
	ds_read_b128 v[38:41], v143 offset:19456
	s_waitcnt lgkmcnt(3)
	v_mfma_f32_16x16x32_bf16 v[14:17], v[10:13], v[78:81], v[74:77]
	v_mfma_f32_16x16x32_bf16 v[22:25], v[10:13], v[90:93], v[86:89]
	s_waitcnt lgkmcnt(1)
	v_mfma_f32_16x16x32_bf16 v[10:13], v[34:37], v[82:85], v[14:17]
	v_mfma_f32_16x16x32_bf16 v[14:17], v[34:37], v[94:97], v[22:25]
	v_mov_b64_e32 v[34:35], s[80:81]
	v_mov_b64_e32 v[36:37], s[82:83]
	v_mfma_f32_16x16x32_bf16 v[22:25], v[18:21], v[78:81], v[74:77]
	v_mfma_f32_16x16x32_bf16 v[18:21], v[18:21], v[90:93], v[86:89]
	s_waitcnt lgkmcnt(0)
	v_mfma_f32_16x16x32_bf16 v[22:25], v[38:41], v[82:85], v[22:25]
	v_mfma_f32_16x16x32_bf16 v[18:21], v[38:41], v[94:97], v[18:21]
	v_mfma_f32_16x16x32_bf16 v[38:41], v[34:37], v[78:81], v[74:77]
	v_mfma_f32_16x16x32_bf16 v[66:69], v[34:37], v[90:93], v[86:89]
	v_mfma_f32_16x16x32_bf16 v[38:41], v[34:37], v[82:85], v[38:41]
	v_mfma_f32_16x16x32_bf16 v[34:37], v[34:37], v[94:97], v[66:69]
	s_nop 5
	v_mov_b64_e32 v[66:67], s[8:9]
	v_mad_i64_i32 v[136:137], s[4:5], v102, s31, v[66:67]
	s_add_u32 s4, s22, s7
	v_mfma_f32_16x16x32_bf16 v[2:5], v[70:73], v[82:85], v[2:5]
	s_addc_u32 s5, s23, s6
	v_mov_b64_e32 v[66:67], s[4:5]
	s_movk_i32 s4, 0x4200
	v_mfma_f32_16x16x32_bf16 v[6:9], v[70:73], v[94:97], v[6:9]
	v_mad_i64_i32 v[138:139], s[4:5], v101, s4, v[66:67]
	s_mov_b32 s4, 0
	s_mov_b32 s8, 0x41000000
	v_lshl_add_u64 v[136:137], v[136:137], 0, v[0:1]
	v_lshl_add_u64 v[138:139], v[138:139], 0, v[0:1]
	s_mov_b64 s[6:7], 0x134a5000
	v_readfirstlane_b32 s100, v142
	v_lshl_add_u64 v[136:137], v[136:137], 0, s[6:7]
	s_mov_b64 s[6:7], 0x1661c180
	v_xor_b32_e32 v228, 0x80000000, v134
	v_lshl_add_u64 v[138:139], v[138:139], 0, s[6:7]
	v_xor_b32_e32 v232, 0x80000000, v135
	v_mov_b32_e32 v229, v228
	v_mov_b32_e32 v230, v228
	v_mov_b32_e32 v231, v228
	v_mov_b32_e32 v233, v232
	v_mov_b32_e32 v234, v232
	v_mov_b32_e32 v235, v232
	v_mov_b32_e32 v236, s80
	v_mov_b32_e32 v237, s80
	v_mov_b32_e32 v238, s80
	v_mov_b32_e32 v239, s80
	s_branch .LBB0_296
